# attention: next query block's Q rows prefetched one block ahead into spare VGPRs
# baseline (speedup 1.0000x reference)
.Lat0_skipld:
	v_lshl_add_u64 v[2:3], s[48:49], 0, v[134:135]
	v_bfe_u32 v34, v36, 5, 1
	v_lshlrev_b64 v[2:3], 10, v[2:3]
	v_lshl_add_u64 v[2:3], s[44:45], 0, v[2:3]
	v_lshlrev_b32_e32 v132, 4, v34
	v_lshl_add_u64 v[2:3], v[2:3], 0, v[132:133]
	s_cmp_lg_u32 s82, 7
	s_cbranch_scc1 .Lat0_qmov
	global_load_dwordx4 v[80:83], v[2:3], off
	global_load_dwordx4 v[84:87], v[2:3], off offset:32
	global_load_dwordx4 v[88:91], v[2:3], off offset:64
	global_load_dwordx4 v[92:95], v[2:3], off offset:96
	s_branch .Lat0_qdone
.Lat0_qmov:
	v_mov_b32_e32 v80, v176
	v_mov_b32_e32 v81, v177
	v_mov_b32_e32 v82, v178
	v_mov_b32_e32 v83, v179
	v_mov_b32_e32 v84, v180
	v_mov_b32_e32 v85, v181
	v_mov_b32_e32 v86, v182
	v_mov_b32_e32 v87, v183
	v_mov_b32_e32 v88, v184
	v_mov_b32_e32 v89, v185
	v_mov_b32_e32 v90, v186
	v_mov_b32_e32 v91, v187
	v_mov_b32_e32 v92, v188
	v_mov_b32_e32 v93, v189
	v_mov_b32_e32 v94, v190
	v_mov_b32_e32 v95, v191
.Lat0_qdone:
	v_ashrrev_i32_e32 v170, 3, v36
	v_and_b32_e32 v171, 7, v36
	v_lshlrev_b32_e32 v172, 3, v171
	v_add_lshl_u32 v173, v170, s12, 9
	v_or3_b32 v172, v173, v172, s78
	s_lshl_b32 s98, s85, 4
	v_lshlrev_b32_e32 v172, 1, v172
	v_or_b32_e32 v173, s12, v37
	s_add_i32 s98, s98, s79
	v_lshl_add_u32 v173, v173, 10, s98
	s_lshl_b32 s99, s82, 18
	v_add_u32_e32 v174, s99, v173
	v_add_u32_e32 v175, s99, v172
	global_load_dwordx4 v[162:165], v175, s[4:5]
	global_load_dwordx4 v[166:169], v174, s[8:9]
	s_cmp_lg_u32 s82, 0
	s_cselect_b32 s98, 0xfffc0000, 0
	s_cselect_b32 s99, -1, 0
	v_lshl_add_u64 v[192:193], v[2:3], 0, s[98:99]
	global_load_dwordx4 v[176:179], v[192:193], off
	global_load_dwordx4 v[180:183], v[192:193], off offset:32
	global_load_dwordx4 v[184:187], v[192:193], off offset:64
	global_load_dwordx4 v[188:191], v[192:193], off offset:96
	v_lshl_add_u32 v2, v36, 2, 0
	s_mov_b64 s[0:1], -1
	s_cmp_lg_u32 s82, 7
	s_cbranch_scc1 .Lat0_skipw
	s_waitcnt vmcnt(10)
	v_add_f32_e32 v3, v4, v5
	ds_write_b32 v2, v3 offset:36864
.Lat0_skipw:
	s_cmp_lt_u32 s82, 4
	s_waitcnt lgkmcnt(0)
	s_barrier
	s_cbranch_scc1 .LBB0_451
	v_cmp_lt_i32_e32 vcc, v138, v139
	v_and_b32_e32 v40, 32, v36
	v_mov_b32_e32 v39, 0
	v_cndmask_b32_e32 v2, v137, v138, vcc
	v_lshlrev_b32_e32 v38, 2, v2
	s_waitcnt vmcnt(8)
	v_lshlrev_b32_e32 v3, 16, v84
	v_lshlrev_b32_e32 v2, 16, v80
	v_and_b32_e32 v5, 0xffff0000, v84
	v_and_b32_e32 v4, 0xffff0000, v80
	v_lshlrev_b32_e32 v7, 16, v85
	v_lshlrev_b32_e32 v6, 16, v81
	v_and_b32_e32 v9, 0xffff0000, v85
	v_and_b32_e32 v8, 0xffff0000, v81
	v_lshlrev_b32_e32 v11, 16, v86
	v_lshlrev_b32_e32 v10, 16, v82
	v_and_b32_e32 v13, 0xffff0000, v86
	v_and_b32_e32 v12, 0xffff0000, v82
	v_lshlrev_b32_e32 v15, 16, v87
	v_lshlrev_b32_e32 v14, 16, v83
	v_and_b32_e32 v17, 0xffff0000, v87
	v_and_b32_e32 v16, 0xffff0000, v83
	s_waitcnt vmcnt(6)
	v_lshlrev_b32_e32 v19, 16, v92
	v_lshlrev_b32_e32 v18, 16, v88
	v_and_b32_e32 v21, 0xffff0000, v92
	v_and_b32_e32 v20, 0xffff0000, v88
	v_lshlrev_b32_e32 v23, 16, v93
	v_lshlrev_b32_e32 v22, 16, v89
	v_and_b32_e32 v25, 0xffff0000, v93
	v_and_b32_e32 v24, 0xffff0000, v89
	v_lshlrev_b32_e32 v27, 16, v94
	v_lshlrev_b32_e32 v26, 16, v90
	v_and_b32_e32 v29, 0xffff0000, v94
	v_and_b32_e32 v28, 0xffff0000, v90
	v_lshlrev_b32_e32 v31, 16, v95
	v_lshlrev_b32_e32 v30, 16, v91
	v_and_b32_e32 v33, 0xffff0000, v95
	v_and_b32_e32 v32, 0xffff0000, v91
	v_add_u32_e32 v40, s30, v40
	v_mov_b32_e32 v41, 0xff800000
	s_mov_b32 s6, 0
	v_mov_b32_e32 v42, 0xff800000
	v_mov_b32_e32 v45, 0xff800000
	v_mov_b32_e32 v43, 0
	v_mov_b32_e32 v44, 0

.LBB0_453:
	v_ashrrev_i32_e32 v10, 3, v36
	v_and_b32_e32 v11, 7, v36
	v_lshlrev_b32_e32 v2, 3, v11
	v_add_lshl_u32 v3, v10, s12, 9
	v_or3_b32 v2, v3, v2, s78
	s_lshl_b32 s0, s85, 4
	v_lshlrev_b32_e32 v141, 1, v2
	v_or_b32_e32 v2, s12, v37
	s_add_i32 s0, s0, s79
	v_lshl_add_u32 v142, v2, 10, s0
	s_lshl_b32 s0, s82, 18
	v_add_u32_e32 v6, s0, v142
	v_add_u32_e32 v2, s0, v141
	s_mul_i32 s84, s85, 0x480
	v_lshlrev_b32_e32 v12, 1, v36
	v_lshrrev_b32_e32 v13, 1, v36
	v_and_b32_e32 v143, 51, v36
	v_mul_lo_u32 v144, v10, s31
	v_lshlrev_b32_e32 v145, 4, v11
	v_and_b32_e32 v10, 8, v12
	v_and_b32_e32 v11, 4, v13
	s_add_i32 s1, s84, 0
	s_bitset1_b32 s0, 16
	v_lshl_add_u32 v13, v143, 1, s1
	v_lshlrev_b32_e32 v146, 1, v10
	v_lshlrev_b32_e32 v147, 1, v11
	v_add3_u32 v12, 0, v144, v145
	v_add3_u32 v10, v13, v146, v147
	v_add_u32_e32 v13, s0, v141
	v_add_u32_e32 v11, s0, v142
	s_mov_b64 s[0:1], -1
	s_cmp_gt_i32 s85, -1
	v_or_b32_e32 v148, 32, v132
	v_or_b32_e32 v149, 64, v132
	v_or_b32_e32 v150, 0x60, v132
	s_waitcnt vmcnt(5)
	ds_write_b128 v12, v[162:165]
	s_waitcnt vmcnt(4)
	ds_write_b16 v10, v166 offset:18432
	ds_write_b16_d16_hi v10, v166 offset:18576
	ds_write_b16 v10, v167 offset:18720
	ds_write_b16_d16_hi v10, v167 offset:18864
	ds_write_b16 v10, v168 offset:19008
	ds_write_b16_d16_hi v10, v168 offset:19152
	ds_write_b16 v10, v169 offset:19296
	ds_write_b16_d16_hi v10, v169 offset:19440
	s_waitcnt lgkmcnt(0)
	s_barrier
	global_load_dwordx4 v[96:99], v13, s[4:5]
	global_load_dwordx4 v[100:103], v11, s[8:9]
	s_cbranch_scc1 .LBB0_455
	v_or_b32_e32 v36, 32, v132
	v_or_b32_e32 v37, 64, v132
	v_or_b32_e32 v38, 0x60, v132
	s_mov_b64 s[0:1], 0
